# grid-barrier and panel-norm spin polls without s_sleep (poll period is the load round trip)
# speedup vs baseline: 1.0138x; 1.0138x over previous
.LBB0_168:
	s_nop 0
	global_load_dword v2, v0, s[4:5] offset:32 sc1
	s_waitcnt vmcnt(0)
	v_and_b32_e32 v2, 0xffff0000, v2
	v_cmp_ne_u32_e32 vcc, v2, v1
	s_or_b64 s[6:7], vcc, s[6:7]
	s_andn2_b64 exec, exec, s[6:7]
	s_cbranch_execnz .LBB0_168

.LBB0_175:
	global_load_dword v15, v16, s[6:7] sc1
	global_load_dword v0, v16, s[8:9] sc1
	global_load_dword v1, v16, s[10:11] sc1
	global_load_dword v2, v16, s[12:13] sc1
	global_load_dword v3, v16, s[14:15] sc1
	global_load_dword v4, v16, s[16:17] sc1
	global_load_dword v5, v16, s[18:19] sc1
	global_load_dword v6, v16, s[20:21] sc1
	global_load_dword v7, v16, s[22:23] sc1
	global_load_dword v8, v16, s[24:25] sc1
	global_load_dword v9, v16, s[26:27] sc1
	global_load_dword v10, v16, s[28:29] sc1
	global_load_dword v11, v16, s[30:31] sc1
	global_load_dword v12, v16, s[34:35] sc1
	global_load_dword v13, v16, s[36:37] sc1
	global_load_dword v14, v16, s[38:39] sc1
	s_mov_b64 s[40:41], -1
	s_mov_b64 s[42:43], -1
	s_waitcnt vmcnt(14)
	v_add_u32_e32 v17, v0, v15
	s_waitcnt vmcnt(13)
	v_add_u32_e32 v17, v17, v1
	s_waitcnt vmcnt(12)
	v_add_u32_e32 v17, v17, v2
	s_waitcnt vmcnt(11)
	v_add_u32_e32 v17, v17, v3
	s_waitcnt vmcnt(10)
	v_add_u32_e32 v17, v17, v4
	s_waitcnt vmcnt(9)
	v_add_u32_e32 v17, v17, v5
	s_waitcnt vmcnt(8)
	v_add_u32_e32 v17, v17, v6
	s_waitcnt vmcnt(7)
	v_add_u32_e32 v17, v17, v7
	s_waitcnt vmcnt(6)
	v_add_u32_e32 v17, v17, v8
	s_waitcnt vmcnt(5)
	v_add_u32_e32 v17, v17, v9
	s_waitcnt vmcnt(4)
	v_add_u32_e32 v17, v17, v10
	s_waitcnt vmcnt(3)
	v_add_u32_e32 v17, v17, v11
	s_waitcnt vmcnt(2)
	v_add_u32_e32 v17, v17, v12
	s_waitcnt vmcnt(1)
	v_add_u32_e32 v17, v17, v13
	s_waitcnt vmcnt(0)
	v_add_u32_e32 v17, v17, v14
	v_cmp_eq_u32_e32 vcc, s46, v17
	s_cbranch_vccnz .LBB0_174
	s_and_b32 s40, s47, 0xff
	s_cmp_eq_u32 s40, 0
	s_mov_b64 s[40:41], -1
	s_mov_b64 s[44:45], -1
	s_nop 0
	s_cbranch_scc1 .LBB0_179
	s_and_b64 vcc, exec, s[44:45]
	s_cbranch_vccz .LBB0_174

.LBB0_193:
	s_and_b32 s20, s24, 0xff
	s_mov_b64 s[18:19], -1
	s_cmp_lg_u32 s20, 0
	s_mov_b64 s[22:23], -1
	s_nop 0
	s_cbranch_scc0 .LBB0_196
	s_and_b64 vcc, exec, s[22:23]
	s_cbranch_vccz .LBB0_192

.LBB0_210:
	s_and_b32 s18, s24, 0xff
	s_cmp_lg_u32 s18, 0
	s_mov_b64 s[20:21], -1
	s_nop 0
	s_cbranch_scc0 .LBB0_213
	s_mov_b64 s[22:23], -1
	s_and_b64 vcc, exec, s[20:21]
	s_cbranch_vccz .LBB0_209

.LBB0_232:
	global_load_dword v15, v16, s[4:5] sc1
	global_load_dword v0, v16, s[6:7] sc1
	global_load_dword v1, v16, s[8:9] sc1
	global_load_dword v2, v16, s[10:11] sc1
	global_load_dword v3, v16, s[12:13] sc1
	global_load_dword v4, v16, s[14:15] sc1
	global_load_dword v5, v16, s[16:17] sc1
	global_load_dword v6, v16, s[18:19] sc1
	global_load_dword v7, v16, s[20:21] sc1
	global_load_dword v8, v16, s[22:23] sc1
	global_load_dword v9, v16, s[24:25] sc1
	global_load_dword v10, v16, s[26:27] sc1
	global_load_dword v11, v16, s[28:29] sc1
	global_load_dword v12, v16, s[30:31] sc1
	global_load_dword v13, v16, s[34:35] sc1
	global_load_dword v14, v16, s[36:37] sc1
	s_mov_b64 s[38:39], -1
	s_mov_b64 s[40:41], -1
	s_waitcnt vmcnt(14)
	v_add_u32_e32 v17, v0, v15
	s_waitcnt vmcnt(13)
	v_add_u32_e32 v17, v17, v1
	s_waitcnt vmcnt(12)
	v_add_u32_e32 v17, v17, v2
	s_waitcnt vmcnt(11)
	v_add_u32_e32 v17, v17, v3
	s_waitcnt vmcnt(10)
	v_add_u32_e32 v17, v17, v4
	s_waitcnt vmcnt(9)
	v_add_u32_e32 v17, v17, v5
	s_waitcnt vmcnt(8)
	v_add_u32_e32 v17, v17, v6
	s_waitcnt vmcnt(7)
	v_add_u32_e32 v17, v17, v7
	s_waitcnt vmcnt(6)
	v_add_u32_e32 v17, v17, v8
	s_waitcnt vmcnt(5)
	v_add_u32_e32 v17, v17, v9
	s_waitcnt vmcnt(4)
	v_add_u32_e32 v17, v17, v10
	s_waitcnt vmcnt(3)
	v_add_u32_e32 v17, v17, v11
	s_waitcnt vmcnt(2)
	v_add_u32_e32 v17, v17, v12
	s_waitcnt vmcnt(1)
	v_add_u32_e32 v17, v17, v13
	s_waitcnt vmcnt(0)
	v_add_u32_e32 v17, v17, v14
	v_cmp_eq_u32_e32 vcc, s44, v17
	s_cbranch_vccnz .LBB0_231
	s_and_b32 s38, s45, 0xff
	s_cmp_eq_u32 s38, 0
	s_mov_b64 s[38:39], -1
	s_mov_b64 s[42:43], -1
	s_nop 0
	s_cbranch_scc1 .LBB0_236
	s_and_b64 vcc, exec, s[42:43]
	s_cbranch_vccz .LBB0_231

.LBB0_250:
	s_and_b32 s18, s22, 0xff
	s_mov_b64 s[16:17], -1
	s_cmp_lg_u32 s18, 0
	s_mov_b64 s[20:21], -1
	s_nop 0
	s_cbranch_scc0 .LBB0_253
	s_and_b64 vcc, exec, s[20:21]
	s_cbranch_vccz .LBB0_249

.LBB0_267:
	s_and_b32 s16, s22, 0xff
	s_cmp_lg_u32 s16, 0
	s_mov_b64 s[18:19], -1
	s_nop 0
	s_cbranch_scc0 .LBB0_270
	s_mov_b64 s[20:21], -1
	s_and_b64 vcc, exec, s[18:19]
	s_cbranch_vccz .LBB0_266

.LBB0_418:
	global_load_dword v0, v129, s[40:41] sc1
	s_mov_b64 s[42:43], -1
	s_waitcnt vmcnt(0)
	v_cmp_lt_u32_e32 vcc, 3, v0
	s_cbranch_vccnz .LBB0_417
	s_nop 0
	global_load_dword v0, v129, s[40:41] sc1
	s_waitcnt vmcnt(0)
	v_cmp_gt_u32_e32 vcc, 4, v0
	s_cbranch_vccz .LBB0_417
	s_nop 0
	global_load_dword v0, v129, s[40:41] sc1
	s_waitcnt vmcnt(0)
	v_cmp_gt_u32_e32 vcc, 4, v0
	s_cbranch_vccz .LBB0_417
	s_nop 0
	global_load_dword v0, v129, s[40:41] sc1
	s_waitcnt vmcnt(0)
	v_cmp_gt_u32_e32 vcc, 4, v0
	s_cbranch_vccz .LBB0_417
	s_nop 0
	global_load_dword v0, v129, s[40:41] sc1
	s_waitcnt vmcnt(0)
	v_cmp_gt_u32_e32 vcc, 4, v0
	s_cbranch_vccz .LBB0_417
	s_add_i32 s44, s44, -5
	s_cmp_eq_u32 s44, 0
	s_cselect_b64 s[42:43], -1, 0
	s_nop 0
	s_branch .LBB0_417

.LBB0_893:
	global_load_dword v15, v16, s[4:5] sc1
	s_waitcnt lgkmcnt(0)
	global_load_dword v0, v16, s[6:7] sc1
	global_load_dword v1, v16, s[8:9] sc1
	global_load_dword v2, v16, s[10:11] sc1
	global_load_dword v3, v16, s[12:13] sc1
	global_load_dword v4, v16, s[14:15] sc1
	global_load_dword v5, v16, s[16:17] sc1
	global_load_dword v6, v16, s[18:19] sc1
	global_load_dword v7, v16, s[20:21] sc1
	global_load_dword v8, v16, s[22:23] sc1
	global_load_dword v9, v16, s[24:25] sc1
	global_load_dword v10, v16, s[26:27] sc1
	global_load_dword v11, v16, s[28:29] sc1
	global_load_dword v12, v16, s[30:31] sc1
	global_load_dword v13, v16, s[34:35] sc1
	global_load_dword v14, v16, s[36:37] sc1
	s_mov_b64 s[38:39], -1
	s_mov_b64 s[40:41], -1
	s_waitcnt vmcnt(14)
	v_add_u32_e32 v17, v0, v15
	s_waitcnt vmcnt(13)
	v_add_u32_e32 v17, v17, v1
	s_waitcnt vmcnt(12)
	v_add_u32_e32 v17, v17, v2
	s_waitcnt vmcnt(11)
	v_add_u32_e32 v17, v17, v3
	s_waitcnt vmcnt(10)
	v_add_u32_e32 v17, v17, v4
	s_waitcnt vmcnt(9)
	v_add_u32_e32 v17, v17, v5
	s_waitcnt vmcnt(8)
	v_add_u32_e32 v17, v17, v6
	s_waitcnt vmcnt(7)
	v_add_u32_e32 v17, v17, v7
	s_waitcnt vmcnt(6)
	v_add_u32_e32 v17, v17, v8
	s_waitcnt vmcnt(5)
	v_add_u32_e32 v17, v17, v9
	s_waitcnt vmcnt(4)
	v_add_u32_e32 v17, v17, v10
	s_waitcnt vmcnt(3)
	v_add_u32_e32 v17, v17, v11
	s_waitcnt vmcnt(2)
	v_add_u32_e32 v17, v17, v12
	s_waitcnt vmcnt(1)
	v_add_u32_e32 v17, v17, v13
	s_waitcnt vmcnt(0)
	v_add_u32_e32 v17, v17, v14
	v_cmp_eq_u32_e32 vcc, s44, v17
	s_cbranch_vccnz .LBB0_892
	s_and_b32 s38, s45, 0xff
	s_cmp_eq_u32 s38, 0
	s_mov_b64 s[38:39], -1
	s_mov_b64 s[42:43], -1
	s_nop 0
	s_cbranch_scc1 .LBB0_897
	s_and_b64 vcc, exec, s[42:43]
	s_cbranch_vccz .LBB0_892

.LBB0_1181:
	global_load_dword v0, v131, s[44:45] sc1
	s_mov_b64 s[48:49], -1
	s_waitcnt vmcnt(0)
	v_cmp_lt_u32_e32 vcc, 3, v0
	s_cbranch_vccnz .LBB0_1180
	s_nop 0
	global_load_dword v0, v131, s[44:45] sc1
	s_waitcnt vmcnt(0)
	v_cmp_gt_u32_e32 vcc, 4, v0
	s_cbranch_vccz .LBB0_1180
	s_nop 0
	global_load_dword v0, v131, s[44:45] sc1
	s_waitcnt vmcnt(0)
	v_cmp_gt_u32_e32 vcc, 4, v0
	s_cbranch_vccz .LBB0_1180
	s_nop 0
	global_load_dword v0, v131, s[44:45] sc1
	s_waitcnt vmcnt(0)
	v_cmp_gt_u32_e32 vcc, 4, v0
	s_cbranch_vccz .LBB0_1180
	s_nop 0
	global_load_dword v0, v131, s[44:45] sc1
	s_waitcnt vmcnt(0)
	v_cmp_gt_u32_e32 vcc, 4, v0
	s_cbranch_vccz .LBB0_1180
	s_add_i32 s50, s50, -5
	s_cmp_eq_u32 s50, 0
	s_cselect_b64 s[48:49], -1, 0
	s_nop 0
	s_branch .LBB0_1180

.LBB0_1491:
	global_load_dword v0, v129, s[38:39] sc1
	s_mov_b64 s[40:41], -1
	s_waitcnt vmcnt(0)
	v_cmp_lt_u32_e32 vcc, 3, v0
	s_cbranch_vccnz .LBB0_1490
	s_nop 0
	global_load_dword v0, v129, s[38:39] sc1
	s_waitcnt vmcnt(0)
	v_cmp_gt_u32_e32 vcc, 4, v0
	s_cbranch_vccz .LBB0_1490
	s_nop 0
	global_load_dword v0, v129, s[38:39] sc1
	s_waitcnt vmcnt(0)
	v_cmp_gt_u32_e32 vcc, 4, v0
	s_cbranch_vccz .LBB0_1490
	s_nop 0
	global_load_dword v0, v129, s[38:39] sc1
	s_waitcnt vmcnt(0)
	v_cmp_gt_u32_e32 vcc, 4, v0
	s_cbranch_vccz .LBB0_1490
	s_nop 0
	global_load_dword v0, v129, s[38:39] sc1
	s_waitcnt vmcnt(0)
	v_cmp_gt_u32_e32 vcc, 4, v0
	s_cbranch_vccz .LBB0_1490
	s_add_i32 s42, s42, -5
	s_cmp_eq_u32 s42, 0
	s_cselect_b64 s[40:41], -1, 0
	s_nop 0
	s_branch .LBB0_1490

.LBB0_2529:
	global_load_dword v0, v129, s[34:35] sc1
	s_mov_b64 s[36:37], -1
	s_waitcnt vmcnt(0)
	v_cmp_lt_u32_e32 vcc, 3, v0
	s_cbranch_vccnz .LBB0_2528
	s_nop 0
	global_load_dword v0, v129, s[34:35] sc1
	s_waitcnt vmcnt(0)
	v_cmp_gt_u32_e32 vcc, 4, v0
	s_cbranch_vccz .LBB0_2528
	s_nop 0
	global_load_dword v0, v129, s[34:35] sc1
	s_waitcnt vmcnt(0)
	v_cmp_gt_u32_e32 vcc, 4, v0
	s_cbranch_vccz .LBB0_2528
	s_nop 0
	global_load_dword v0, v129, s[34:35] sc1
	s_waitcnt vmcnt(0)
	v_cmp_gt_u32_e32 vcc, 4, v0
	s_cbranch_vccz .LBB0_2528
	s_nop 0
	global_load_dword v0, v129, s[34:35] sc1
	s_waitcnt vmcnt(0)
	v_cmp_gt_u32_e32 vcc, 4, v0
	s_cbranch_vccz .LBB0_2528
	s_add_i32 s38, s38, -5
	s_cmp_eq_u32 s38, 0
	s_cselect_b64 s[36:37], -1, 0
	s_nop 0
	s_branch .LBB0_2528
